# C2b unit epilogue: 8 gate loads batched up front with counted vmcnt(7) waits instead of load+vmcnt(0)+store ladder (on top of A1 load fix)
# baseline (speedup 1.0000x reference)
; #define TIDX (tid_launder())
; DI unsigned pack2(float a, float b) { hwf2 v = {a, b}; hwbf2 r = __builtin_convertvector(v, hwbf2); return __builtin_bit_cast(unsigned, r); }
; DI void store_y(const f32x16 (&o)[2], bf16_t* yrow) {
;   const int lane = TIDX & 63, hh = lane >> 5;
; #pragma unroll
;   for (int dt = 0; dt < 2; ++dt)
; #pragma unroll
;     for (int g = 0; g < 4; ++g) {
;       bf16_t* ptr = yrow + dt * 32 + 8 * g + 4 * hh;
;       const uint2 z = *(const uint2*)ptr;
;       uint2 w;
;       w.x = pack2(o[dt][4 * g + 0] * __uint_as_float(z.x << 16), o[dt][4 * g + 1] * __uint_as_float(z.x & 0xffff0000u));
;       w.y = pack2(o[dt][4 * g + 2] * __uint_as_float(z.y << 16), o[dt][4 * g + 3] * __uint_as_float(z.y & 0xffff0000u));
;       *(uint2*)ptr = w;
;     }
; }
.LBB0_28:
	v_mov_b32_e32 v0, v230
	v_lshlrev_b64 v[2:3], 11, v[164:165]
	v_lshrrev_b32_e32 v0, 2, v0
	v_lshl_add_u64 v[2:3], v[138:139], 0, v[2:3]
	v_and_b32_e32 v0, 8, v0
	v_lshl_add_u64 v[2:3], v[2:3], 0, v[0:1]
	global_load_dwordx2 v[34:35], v[2:3], off offset:1536
	global_load_dwordx2 v[36:37], v[2:3], off offset:1552
	global_load_dwordx2 v[38:39], v[2:3], off offset:1568
	global_load_dwordx2 v[40:41], v[2:3], off offset:1584
	global_load_dwordx2 v[42:43], v[2:3], off offset:1600
	global_load_dwordx2 v[44:45], v[2:3], off offset:1616
	global_load_dwordx2 v[46:47], v[2:3], off offset:1632
	global_load_dwordx2 v[48:49], v[2:3], off offset:1648
	v_add_u32_e32 v133, s94, v133
	v_cmp_lt_i32_e32 vcc, s43, v133
	s_or_b64 s[68:69], vcc, s[68:69]
	s_waitcnt vmcnt(7)
	v_lshlrev_b32_e32 v6, 16, v34
	v_and_b32_e32 v7, 0xffff0000, v34
	v_pk_mul_f32 v[6:7], v[184:185], v[6:7]
	v_lshlrev_b32_e32 v4, 16, v35
	v_and_b32_e32 v5, 0xffff0000, v35
	v_pk_mul_f32 v[4:5], v[180:181], v[4:5]
	v_cvt_pk_bf16_f32 v34, v6, v7
	v_cvt_pk_bf16_f32 v35, v4, v5
	global_store_dwordx2 v[2:3], v[34:35], off offset:1536
	s_waitcnt vmcnt(7)
	v_lshlrev_b32_e32 v6, 16, v36
	v_and_b32_e32 v7, 0xffff0000, v36
	v_pk_mul_f32 v[6:7], v[168:169], v[6:7]
	v_lshlrev_b32_e32 v4, 16, v37
	v_and_b32_e32 v5, 0xffff0000, v37
	v_pk_mul_f32 v[4:5], v[166:167], v[4:5]
	v_cvt_pk_bf16_f32 v36, v6, v7
	v_cvt_pk_bf16_f32 v37, v4, v5
	global_store_dwordx2 v[2:3], v[36:37], off offset:1552
	s_waitcnt vmcnt(7)
	v_lshlrev_b32_e32 v6, 16, v38
	v_and_b32_e32 v7, 0xffff0000, v38
	v_pk_mul_f32 v[6:7], v[162:163], v[6:7]
	v_lshlrev_b32_e32 v4, 16, v39
	v_and_b32_e32 v5, 0xffff0000, v39
	v_pk_mul_f32 v[4:5], v[160:161], v[4:5]
	v_cvt_pk_bf16_f32 v38, v6, v7
	v_cvt_pk_bf16_f32 v39, v4, v5
	global_store_dwordx2 v[2:3], v[38:39], off offset:1568
	s_waitcnt vmcnt(7)
	v_lshlrev_b32_e32 v6, 16, v40
	v_and_b32_e32 v7, 0xffff0000, v40
	v_pk_mul_f32 v[6:7], v[158:159], v[6:7]
	v_lshlrev_b32_e32 v4, 16, v41
	v_and_b32_e32 v5, 0xffff0000, v41
	v_pk_mul_f32 v[4:5], v[156:157], v[4:5]
	v_cvt_pk_bf16_f32 v40, v6, v7
	v_cvt_pk_bf16_f32 v41, v4, v5
	global_store_dwordx2 v[2:3], v[40:41], off offset:1584
	s_waitcnt vmcnt(7)
	v_lshlrev_b32_e32 v6, 16, v42
	v_and_b32_e32 v7, 0xffff0000, v42
	v_pk_mul_f32 v[6:7], v[154:155], v[6:7]
	v_lshlrev_b32_e32 v4, 16, v43
	v_and_b32_e32 v5, 0xffff0000, v43
	v_pk_mul_f32 v[4:5], v[152:153], v[4:5]
	v_cvt_pk_bf16_f32 v42, v6, v7
	v_cvt_pk_bf16_f32 v43, v4, v5
	global_store_dwordx2 v[2:3], v[42:43], off offset:1600
	s_waitcnt vmcnt(7)
	v_lshlrev_b32_e32 v6, 16, v44
	v_and_b32_e32 v7, 0xffff0000, v44
	v_pk_mul_f32 v[6:7], v[150:151], v[6:7]
	v_lshlrev_b32_e32 v4, 16, v45
	v_and_b32_e32 v5, 0xffff0000, v45
	v_pk_mul_f32 v[4:5], v[148:149], v[4:5]
	v_cvt_pk_bf16_f32 v44, v6, v7
	v_cvt_pk_bf16_f32 v45, v4, v5
	global_store_dwordx2 v[2:3], v[44:45], off offset:1616
	s_waitcnt vmcnt(7)
	v_lshlrev_b32_e32 v6, 16, v46
	v_and_b32_e32 v7, 0xffff0000, v46
	v_pk_mul_f32 v[6:7], v[146:147], v[6:7]
	v_lshlrev_b32_e32 v4, 16, v47
	v_and_b32_e32 v5, 0xffff0000, v47
	v_pk_mul_f32 v[4:5], v[144:145], v[4:5]
	v_cvt_pk_bf16_f32 v46, v6, v7
	v_cvt_pk_bf16_f32 v47, v4, v5
	global_store_dwordx2 v[2:3], v[46:47], off offset:1632
	s_waitcnt vmcnt(7)
	v_lshlrev_b32_e32 v6, 16, v48
	v_and_b32_e32 v7, 0xffff0000, v48
	v_pk_mul_f32 v[6:7], v[142:143], v[6:7]
	v_lshlrev_b32_e32 v4, 16, v49
	v_and_b32_e32 v5, 0xffff0000, v49
	v_pk_mul_f32 v[4:5], v[140:141], v[4:5]
	v_cvt_pk_bf16_f32 v48, v6, v7
	v_cvt_pk_bf16_f32 v49, v4, v5
	global_store_dwordx2 v[2:3], v[48:49], off offset:1648
	s_andn2_b64 exec, exec, s[68:69]
	s_cbranch_execz .LBB0_84
